# conv: 31-tap pk_fma chains interleaved pairwise (no s_nop between dependent packed FMAs), LayerNorm partial reductions with private temporaries; rsqrt denormal rescue removed where the argument is >=
# baseline (speedup 1.0000x reference)
; DI unsigned pk2(float a, float b) { fl2_t f = {a, b}; bf2_t r = __builtin_convertvector(f, bf2_t); return __builtin_bit_cast(unsigned, r); }
; DI void conv_item(const Params& p, char* lds, int t0, int tid) {
;     ...
; #pragma unroll
;     for (int i = 0; i < 8; ++i) {
;       const float s1 = red[(0 * 8 + i) * 2] + red[(1 * 8 + i) * 2] + red[(2 * 8 + i) * 2] + red[(3 * 8 + i) * 2];
;       const float s2 = red[(0 * 8 + i) * 2 + 1] + red[(1 * 8 + i) * 2 + 1] + red[(2 * 8 + i) * 2 + 1] + red[(3 * 8 + i) * 2 + 1];
;       const float mu = s1 * (1.f / 512.f);
;       const float var = fmaxf(s2 * (1.f / 512.f) - mu * mu, 0.f);
;       const float rstd = rsqrtf(var + 1e-6f);
;       float a = (ya[i] - mu) * rstd * gl.x + bl.x, b = (yb[i] - mu) * rstd * gl.y + bl.y;
;       a = a / (1.f + __expf(-a)); b = b / (1.f + __expf(-b));
;       Hu[((size_t)(t0 + ps * 8 + i) * D + 512) / 2 + tid] = pk2(a, b);
;     }
.LBB0_195:
	s_or_b64 exec, exec, s[6:7]
	s_waitcnt lgkmcnt(0)
	s_barrier
	ds_read_b128 v[160:163], v220 offset:63552
	ds_read_b128 v[166:169], v220 offset:63488
	ds_read_b128 v[6:9], v220 offset:63504
	ds_read_b128 v[170:173], v220 offset:63616
	ds_read_b128 v[174:177], v220 offset:63680
	ds_read_b128 v[178:181], v220 offset:63568
	s_waitcnt lgkmcnt(4)
	v_pk_add_f32 v[4:5], v[166:167], v[160:161]
	v_pk_add_f32 v[162:163], v[168:169], v[162:163]
	s_waitcnt lgkmcnt(2)
	v_pk_add_f32 v[4:5], v[4:5], v[170:171]
	v_pk_add_f32 v[162:163], v[162:163], v[172:173]
	s_waitcnt lgkmcnt(1)
	v_pk_add_f32 v[4:5], v[4:5], v[174:175]
	v_pk_add_f32 v[162:163], v[162:163], v[176:177]
	v_pk_mul_f32 v[4:5], v[4:5], s[0:1] op_sel_hi:[1,0]
	v_pk_mul_f32 v[162:163], v[162:163], s[0:1] op_sel_hi:[1,0]
	v_fma_f32 v160, -v4, v4, v5
	v_max_f32_e32 v160, 0, v160
	v_add_f32_e32 v160, 0x358637bd, v160
	v_pk_add_f32 v[2:3], v[2:3], v[4:5] op_sel_hi:[1,0] neg_lo:[0,1] neg_hi:[0,1]
	v_fma_f32 v168, -v162, v162, v163
	v_rsq_f32_e32 v160, v160
	v_max_f32_e32 v168, 0, v168
	v_add_f32_e32 v168, 0x358637bd, v168
	v_pk_mul_f32 v[2:3], v[2:3], v[160:161] op_sel_hi:[1,0]
	v_pk_add_f32 v[156:157], v[156:157], v[162:163] op_sel_hi:[1,0] neg_lo:[0,1] neg_hi:[0,1]
	v_pk_fma_f32 v[166:167], v[144:145], v[2:3], v[146:147]
	v_add_u32_e32 v160, s8, v1
	v_mul_f32_e32 v2, 0xbfb8aa3b, v166
	v_mul_f32_e32 v3, 0xbfb8aa3b, v167
	v_exp_f32_e32 v2, v2
	v_exp_f32_e32 v3, v3
	ds_read_b128 v[182:185], v220 offset:63632
	ds_read_b128 v[186:189], v220 offset:63696
	s_waitcnt lgkmcnt(2)
	v_pk_add_f32 v[6:7], v[6:7], v[178:179]
	v_pk_add_f32 v[170:171], v[2:3], 1.0 op_sel_hi:[1,0]
	v_pk_add_f32 v[8:9], v[8:9], v[180:181]
	s_waitcnt lgkmcnt(1)
	v_pk_add_f32 v[6:7], v[6:7], v[182:183]
	v_pk_add_f32 v[8:9], v[8:9], v[184:185]
	s_waitcnt lgkmcnt(0)
	v_pk_add_f32 v[6:7], v[6:7], v[186:187]
	v_rcp_f32_e32 v161, v171
	s_nop 0
	v_mul_f32_e32 v161, v167, v161
	v_rsq_f32_e32 v168, v168
	v_rcp_f32_e32 v167, v170
	s_nop 0
	v_mul_f32_e32 v167, v166, v167
	v_mov_b32_e32 v166, v168
	v_pk_mul_f32 v[156:157], v[156:157], v[166:167] op_sel_hi:[1,0]
	v_cvt_pk_bf16_f32 v168, v167, v161
	v_pk_fma_f32 v[156:157], v[144:145], v[156:157], v[146:147]
	v_ashrrev_i32_e32 v161, 31, v160
	v_mul_f32_e32 v162, 0xbfb8aa3b, v156
	v_mul_f32_e32 v163, 0xbfb8aa3b, v157
	v_exp_f32_e32 v162, v162
	v_exp_f32_e32 v163, v163
	v_lshlrev_b64 v[166:167], 11, v[160:161]
	v_and_b32_e32 v166, 0xffffc000, v166
	v_lshl_add_u64 v[166:167], v[78:79], 0, v[166:167]
	v_pk_add_f32 v[162:163], v[162:163], 1.0 op_sel_hi:[1,0]
	global_store_dword v[166:167], v168, off
	v_pk_mul_f32 v[6:7], v[6:7], s[0:1] op_sel_hi:[1,0]
	v_pk_add_f32 v[8:9], v[8:9], v[188:189]
	ds_read_b128 v[2:5], v220 offset:63520
	v_rcp_f32_e32 v161, v163
	s_nop 0
	v_mul_f32_e32 v161, v157, v161
	v_pk_mul_f32 v[8:9], v[8:9], s[0:1] op_sel_hi:[1,0]
	v_fma_f32 v166, -v6, v6, v7
	v_max_f32_e32 v166, 0, v166
	v_add_f32_e32 v166, 0x358637bd, v166
	v_rcp_f32_e32 v157, v162
	s_nop 0
	v_mul_f32_e32 v162, v156, v157
	v_rsq_f32_e32 v166, v166
	v_pk_add_f32 v[6:7], v[158:159], v[6:7] op_sel_hi:[1,0] neg_lo:[0,1] neg_hi:[0,1]
	v_cvt_pk_bf16_f32 v161, v162, v161
	v_add_u32_e32 v158, 1, v160
	v_mov_b32_e32 v156, v166
	v_pk_mul_f32 v[6:7], v[6:7], v[156:157] op_sel_hi:[1,0]
	v_ashrrev_i32_e32 v159, 31, v158
	v_pk_fma_f32 v[6:7], v[144:145], v[6:7], v[146:147]
	v_lshlrev_b64 v[158:159], 11, v[158:159]
	v_mul_f32_e32 v156, 0xbfb8aa3b, v6
	v_mul_f32_e32 v157, 0xbfb8aa3b, v7
	v_exp_f32_e32 v156, v156
	v_exp_f32_e32 v157, v157
	v_lshl_add_u64 v[158:159], v[78:79], 0, v[158:159]
	global_store_dword v[158:159], v161, off
	s_add_i32 s8, s8, 8
	v_pk_add_f32 v[156:157], v[156:157], 1.0 op_sel_hi:[1,0]
	v_add_u32_e32 v238, 0x2000, v238
	s_cmp_lg_u32 s8, 32
	v_rcp_f32_e32 v158, v157
	s_nop 0
	v_mul_f32_e32 v157, v7, v158
	v_fma_f32 v159, -v8, v8, v9
	v_max_f32_e32 v159, 0, v159
	v_add_f32_e32 v159, 0x358637bd, v159
	v_rcp_f32_e32 v7, v156
	s_nop 0
	v_mul_f32_e32 v156, v6, v7
	v_rsq_f32_e32 v159, v159
	v_pk_add_f32 v[8:9], v[164:165], v[8:9] op_sel_hi:[1,0] neg_lo:[0,1] neg_hi:[0,1]
	v_cvt_pk_bf16_f32 v156, v156, v157
	v_mov_b32_e32 v6, v159
	v_pk_mul_f32 v[6:7], v[8:9], v[6:7] op_sel_hi:[1,0]
	v_add_u32_e32 v8, 2, v160
	v_pk_fma_f32 v[182:183], v[144:145], v[6:7], v[146:147]
	v_ashrrev_i32_e32 v9, 31, v8
	v_mul_f32_e32 v6, 0xbfb8aa3b, v182
	v_mul_f32_e32 v7, 0xbfb8aa3b, v183
	v_exp_f32_e32 v6, v6
	v_exp_f32_e32 v7, v7
	s_nop 0
	v_pk_add_f32 v[184:185], v[6:7], 1.0 op_sel_hi:[1,0]
	s_nop 0
	v_lshlrev_b64 v[6:7], 11, v[8:9]
	v_lshl_add_u64 v[6:7], v[78:79], 0, v[6:7]
	global_store_dword v[6:7], v156, off
	v_rcp_f32_e32 v6, v185
	s_nop 0
	v_mul_f32_e32 v183, v183, v6
	ds_read_b128 v[6:9], v220 offset:63584
	ds_read_b128 v[156:159], v220 offset:63648
	ds_read_b128 v[162:165], v220 offset:63712
	ds_read_b128 v[166:169], v220 offset:63536
	ds_read_b128 v[170:173], v220 offset:63600
	s_waitcnt lgkmcnt(4)
	v_pk_add_f32 v[2:3], v[2:3], v[6:7]
	v_pk_add_f32 v[4:5], v[4:5], v[8:9]
	s_waitcnt lgkmcnt(3)
	v_pk_add_f32 v[2:3], v[2:3], v[156:157]
	v_pk_add_f32 v[4:5], v[4:5], v[158:159]
	s_waitcnt lgkmcnt(2)
; DI unsigned pk2(float a, float b) { fl2_t f = {a, b}; bf2_t r = __builtin_convertvector(f, bf2_t); return __builtin_bit_cast(unsigned, r); }
; DI void conv_item(const Params& p, char* lds, int t0, int tid) {
;     ...
; #pragma unroll
;     for (int i = 0; i < 8; ++i) {
;       const float s1 = red[(0 * 8 + i) * 2] + red[(1 * 8 + i) * 2] + red[(2 * 8 + i) * 2] + red[(3 * 8 + i) * 2];
;       const float s2 = red[(0 * 8 + i) * 2 + 1] + red[(1 * 8 + i) * 2 + 1] + red[(2 * 8 + i) * 2 + 1] + red[(3 * 8 + i) * 2 + 1];
;       const float mu = s1 * (1.f / 512.f);
;       const float var = fmaxf(s2 * (1.f / 512.f) - mu * mu, 0.f);
;       const float rstd = rsqrtf(var + 1e-6f);
;       float a = (ya[i] - mu) * rstd * gl.x + bl.x, b = (yb[i] - mu) * rstd * gl.y + bl.y;
;       a = a / (1.f + __expf(-a)); b = b / (1.f + __expf(-b));
;       Hu[((size_t)(t0 + ps * 8 + i) * D + 512) / 2 + tid] = pk2(a, b);
;     }
;     __syncthreads();
	v_pk_add_f32 v[2:3], v[2:3], v[162:163]
	v_pk_add_f32 v[4:5], v[4:5], v[164:165]
	v_pk_mul_f32 v[2:3], v[2:3], s[0:1] op_sel_hi:[1,0]
	v_pk_mul_f32 v[4:5], v[4:5], s[0:1] op_sel_hi:[1,0]
	v_fma_f32 v6, -v2, v2, v3
	v_max_f32_e32 v6, 0, v6
	v_add_f32_e32 v6, 0x358637bd, v6
	v_pk_add_f32 v[2:3], v[148:149], v[2:3] op_sel_hi:[1,0] neg_lo:[0,1] neg_hi:[0,1]
	v_add_u32_e32 v148, 3, v160
	v_rsq_f32_e32 v6, v6
	v_rcp_f32_e32 v7, v184
	s_nop 0
	v_mul_f32_e32 v156, v182, v7
	v_ashrrev_i32_e32 v149, 31, v148
	v_pk_mul_f32 v[2:3], v[2:3], v[6:7] op_sel_hi:[1,0]
	v_lshlrev_b64 v[148:149], 11, v[148:149]
	v_pk_fma_f32 v[2:3], v[144:145], v[2:3], v[146:147]
	v_cvt_pk_bf16_f32 v156, v156, v183
	v_mul_f32_e32 v6, 0xbfb8aa3b, v2
	v_mul_f32_e32 v7, 0xbfb8aa3b, v3
	v_exp_f32_e32 v6, v6
	v_exp_f32_e32 v7, v7
	v_lshl_add_u64 v[148:149], v[78:79], 0, v[148:149]
	global_store_dword v[148:149], v156, off
	v_fma_f32 v8, -v4, v4, v5
	v_pk_add_f32 v[6:7], v[6:7], 1.0 op_sel_hi:[1,0]
	v_max_f32_e32 v8, 0, v8
	v_add_f32_e32 v8, 0x358637bd, v8
	v_pk_add_f32 v[4:5], v[150:151], v[4:5] op_sel_hi:[1,0] neg_lo:[0,1] neg_hi:[0,1]
	v_rcp_f32_e32 v148, v7
	s_nop 0
	v_mul_f32_e32 v7, v3, v148
	v_rsq_f32_e32 v8, v8
	v_rcp_f32_e32 v3, v6
	s_nop 0
	v_mul_f32_e32 v6, v2, v3
	v_mov_b32_e32 v2, v8
	v_pk_mul_f32 v[2:3], v[4:5], v[2:3] op_sel_hi:[1,0]
	v_cvt_pk_bf16_f32 v8, v6, v7
	v_pk_fma_f32 v[2:3], v[144:145], v[2:3], v[146:147]
	v_add_u32_e32 v6, 4, v160
	v_mul_f32_e32 v4, 0xbfb8aa3b, v2
	v_mul_f32_e32 v5, 0xbfb8aa3b, v3
	v_exp_f32_e32 v4, v4
	v_exp_f32_e32 v5, v5
	v_ashrrev_i32_e32 v7, 31, v6
	v_lshlrev_b64 v[6:7], 11, v[6:7]
	v_lshl_add_u64 v[6:7], v[78:79], 0, v[6:7]
	v_pk_add_f32 v[4:5], v[4:5], 1.0 op_sel_hi:[1,0]
	global_store_dword v[6:7], v8, off
	ds_read_b128 v[174:177], v220 offset:63664
	ds_read_b128 v[178:181], v220 offset:63728
	v_rcp_f32_e32 v6, v5
	s_nop 0
	v_mul_f32_e32 v148, v3, v6
	s_waitcnt lgkmcnt(2)
	v_pk_add_f32 v[6:7], v[166:167], v[170:171]
	s_waitcnt lgkmcnt(1)
	v_pk_add_f32 v[6:7], v[6:7], v[174:175]
	s_waitcnt lgkmcnt(0)
	v_pk_add_f32 v[6:7], v[6:7], v[178:179]
	v_rcp_f32_e32 v3, v4
	s_nop 0
	v_mul_f32_e32 v9, v2, v3
	v_pk_mul_f32 v[6:7], v[6:7], s[0:1] op_sel_hi:[1,0]
	s_nop 0
	v_fma_f32 v8, -v6, v6, v7
	v_max_f32_e32 v8, 0, v8
	v_add_f32_e32 v8, 0x358637bd, v8
	v_pk_add_f32 v[4:5], v[152:153], v[6:7] op_sel_hi:[1,0] neg_lo:[0,1] neg_hi:[0,1]
	v_add_u32_e32 v6, 5, v160
	v_rsq_f32_e32 v8, v8
	v_ashrrev_i32_e32 v7, 31, v6
	v_lshlrev_b64 v[6:7], 11, v[6:7]
	v_lshl_add_u64 v[6:7], v[78:79], 0, v[6:7]
	v_mov_b32_e32 v2, v8
	v_pk_mul_f32 v[2:3], v[4:5], v[2:3] op_sel_hi:[1,0]
	v_cvt_pk_bf16_f32 v8, v9, v148
	v_pk_fma_f32 v[2:3], v[144:145], v[2:3], v[146:147]
	global_store_dword v[6:7], v8, off
	v_mul_f32_e32 v4, 0xbfb8aa3b, v2
	v_mul_f32_e32 v5, 0xbfb8aa3b, v3
	v_exp_f32_e32 v4, v4
	v_exp_f32_e32 v5, v5
	s_nop 0
	v_pk_add_f32 v[4:5], v[4:5], 1.0 op_sel_hi:[1,0]
	s_nop 0
	s_nop 0
	v_rcp_f32_e32 v6, v5
	s_nop 0
	v_mul_f32_e32 v148, v3, v6
	v_pk_add_f32 v[6:7], v[168:169], v[172:173]
	v_pk_add_f32 v[6:7], v[6:7], v[176:177]
	v_pk_add_f32 v[6:7], v[6:7], v[180:181]
	v_rcp_f32_e32 v3, v4
	s_nop 0
	v_mul_f32_e32 v9, v2, v3
	v_pk_mul_f32 v[6:7], v[6:7], s[0:1] op_sel_hi:[1,0]
	s_nop 0
	v_fma_f32 v8, -v6, v6, v7
	v_max_f32_e32 v8, 0, v8
	v_add_f32_e32 v8, 0x358637bd, v8
	v_pk_add_f32 v[4:5], v[154:155], v[6:7] op_sel_hi:[1,0] neg_lo:[0,1] neg_hi:[0,1]
	v_add_u32_e32 v6, 6, v160
	v_rsq_f32_e32 v8, v8
	v_ashrrev_i32_e32 v7, 31, v6
	v_lshlrev_b64 v[6:7], 11, v[6:7]
	v_lshl_add_u64 v[6:7], v[78:79], 0, v[6:7]
	v_mov_b32_e32 v2, v8
	v_pk_mul_f32 v[2:3], v[4:5], v[2:3] op_sel_hi:[1,0]
	v_cvt_pk_bf16_f32 v8, v9, v148
	v_pk_fma_f32 v[2:3], v[144:145], v[2:3], v[146:147]
	global_store_dword v[6:7], v8, off
	v_mul_f32_e32 v4, 0xbfb8aa3b, v2
	v_mul_f32_e32 v5, 0xbfb8aa3b, v3
	v_exp_f32_e32 v4, v4
	v_exp_f32_e32 v5, v5
	s_nop 0
	v_pk_add_f32 v[4:5], v[4:5], 1.0 op_sel_hi:[1,0]
	s_nop 0
	s_nop 0
	v_rcp_f32_e32 v6, v5
	s_nop 0
	v_mul_f32_e32 v3, v3, v6
	v_rcp_f32_e32 v5, v4
	s_nop 0
	v_mul_f32_e32 v2, v2, v5
	v_cvt_pk_bf16_f32 v4, v2, v3
	v_add_u32_e32 v2, 7, v160
	v_ashrrev_i32_e32 v3, 31, v2
	v_lshlrev_b64 v[2:3], 11, v[2:3]
	v_lshl_add_u64 v[2:3], v[78:79], 0, v[2:3]
	global_store_dword v[2:3], v4, off
	s_barrier
	s_cbranch_scc0 .LBB0_189
; DI void conv_item(const Params& p, char* lds, int t0, int tid) {
;     ...
;   for (int ps = 0; ps < 4; ++ps) {
;     float za[38], zb[38];
; #pragma unroll
;     for (int rr = 0; rr < 38; ++rr) {
;       const unsigned u = zl[(ps * 8 + rr) * 256 + tid];
;       za[rr] = __uint_as_float(u << 16); zb[rr] = __uint_as_float(u & 0xffff0000u);
;     }
;     float ya[8], yb[8];
; #pragma unroll
;     for (int i = 0; i < 8; ++i) {
;       float a = bias.x, b = bias.y;
; #pragma unroll
;       for (int j = 0; j < 31; ++j) { a += wa[j] * za[i + j]; b += wb[j] * zb[i + j]; }
;       ya[i] = a; yb[i] = b;
.LBB0_196:
	ds_read2st64_b32 v[2:3], v238 offset1:4
	ds_read2st64_b32 v[4:5], v238 offset0:8 offset1:12
	ds_read2st64_b32 v[160:161], v238 offset0:40 offset1:44
	ds_read2st64_b32 v[170:171], v238 offset0:56 offset1:60
	ds_read2st64_b32 v[178:179], v238 offset0:72 offset1:76
	s_waitcnt lgkmcnt(4)
	v_lshlrev_b32_e32 v204, 16, v2
	v_and_b32_e32 v205, 0xffff0000, v2
	v_lshlrev_b32_e32 v156, 16, v3
	v_and_b32_e32 v157, 0xffff0000, v3
	ds_read2st64_b32 v[2:3], v238 offset0:16 offset1:20
	s_waitcnt lgkmcnt(4)
	v_lshlrev_b32_e32 v158, 16, v4
	v_and_b32_e32 v159, 0xffff0000, v4
	v_lshlrev_b32_e32 v164, 16, v5
	v_and_b32_e32 v165, 0xffff0000, v5
	s_waitcnt lgkmcnt(0)
	v_lshlrev_b32_e32 v148, 16, v2
	v_and_b32_e32 v149, 0xffff0000, v2
	v_lshlrev_b32_e32 v150, 16, v3
	v_and_b32_e32 v151, 0xffff0000, v3
	ds_read2st64_b32 v[2:3], v238 offset0:32 offset1:36
	ds_read2st64_b32 v[4:5], v238 offset0:24 offset1:28
	v_lshlrev_b32_e32 v154, 16, v160
	v_and_b32_e32 v155, 0xffff0000, v160
	v_lshlrev_b32_e32 v160, 16, v161
	s_waitcnt lgkmcnt(1)
	v_lshlrev_b32_e32 v6, 16, v2
	v_and_b32_e32 v7, 0xffff0000, v2
	v_lshlrev_b32_e32 v8, 16, v3
	v_and_b32_e32 v9, 0xffff0000, v3
	ds_read2st64_b32 v[2:3], v238 offset0:48 offset1:52
	s_waitcnt lgkmcnt(1)
	v_lshlrev_b32_e32 v152, 16, v4
	v_and_b32_e32 v153, 0xffff0000, v4
	v_lshlrev_b32_e32 v4, 16, v5
	v_and_b32_e32 v5, 0xffff0000, v5
	s_waitcnt lgkmcnt(0)
	v_lshlrev_b32_e32 v162, 16, v2
	v_and_b32_e32 v163, 0xffff0000, v2
	v_lshlrev_b32_e32 v166, 16, v3
	v_and_b32_e32 v167, 0xffff0000, v3
	ds_read2st64_b32 v[2:3], v238 offset0:64 offset1:68
	v_and_b32_e32 v161, 0xffff0000, v161
	v_lshlrev_b32_e32 v168, 16, v170
	v_and_b32_e32 v169, 0xffff0000, v170
	v_lshlrev_b32_e32 v170, 16, v171
	s_waitcnt lgkmcnt(0)
	v_lshlrev_b32_e32 v172, 16, v2
	v_and_b32_e32 v173, 0xffff0000, v2
	v_lshlrev_b32_e32 v174, 16, v3
	v_and_b32_e32 v175, 0xffff0000, v3
	ds_read2st64_b32 v[2:3], v238 offset0:80 offset1:84
	v_and_b32_e32 v171, 0xffff0000, v171
	ds_read2st64_b32 v[186:187], v238 offset0:88 offset1:92
	v_lshlrev_b32_e32 v176, 16, v178
	v_and_b32_e32 v177, 0xffff0000, v178
	s_waitcnt lgkmcnt(1)
	v_lshlrev_b32_e32 v180, 16, v2
	v_and_b32_e32 v181, 0xffff0000, v2
	v_lshlrev_b32_e32 v182, 16, v3
	v_and_b32_e32 v183, 0xffff0000, v3
	ds_read2st64_b32 v[2:3], v238 offset0:96 offset1:100
	v_lshlrev_b32_e32 v178, 16, v179
	v_and_b32_e32 v179, 0xffff0000, v179
	ds_read2st64_b32 v[194:195], v238 offset0:104 offset1:108
	s_waitcnt lgkmcnt(2)
	v_lshlrev_b32_e32 v184, 16, v186
	s_waitcnt lgkmcnt(1)
	v_lshlrev_b32_e32 v188, 16, v2
	v_and_b32_e32 v189, 0xffff0000, v2
	v_lshlrev_b32_e32 v190, 16, v3
	v_and_b32_e32 v191, 0xffff0000, v3
	ds_read2st64_b32 v[2:3], v238 offset0:112 offset1:116
	v_and_b32_e32 v185, 0xffff0000, v186
	v_lshlrev_b32_e32 v186, 16, v187
	v_and_b32_e32 v187, 0xffff0000, v187
	ds_read2st64_b32 v[202:203], v238 offset0:120 offset1:124
	s_waitcnt lgkmcnt(1)
	v_lshlrev_b32_e32 v196, 16, v2
	v_and_b32_e32 v197, 0xffff0000, v2
	v_lshlrev_b32_e32 v198, 16, v3
	v_and_b32_e32 v199, 0xffff0000, v3
	v_pk_fma_f32 v[2:3], v[122:123], v[204:205], v[128:129]
	v_lshlrev_b32_e32 v192, 16, v194
	v_pk_fma_f32 v[2:3], v[124:125], v[156:157], v[2:3]
	ds_read2st64_b32 v[208:209], v238 offset0:128 offset1:132
	ds_read2st64_b32 v[210:211], v238 offset0:136 offset1:140
	ds_read2st64_b32 v[204:205], v238 offset0:144 offset1:148
	v_pk_fma_f32 v[156:157], v[122:123], v[156:157], v[128:129]
	v_and_b32_e32 v193, 0xffff0000, v194
	v_pk_fma_f32 v[2:3], v[126:127], v[158:159], v[2:3]
	v_lshlrev_b32_e32 v194, 16, v195
	v_pk_fma_f32 v[2:3], v[120:121], v[164:165], v[2:3]
	v_and_b32_e32 v195, 0xffff0000, v195
	v_pk_fma_f32 v[2:3], v[80:81], v[148:149], v[2:3]
	s_waitcnt lgkmcnt(0)
	v_lshlrev_b32_e32 v200, 16, v202
	v_pk_fma_f32 v[2:3], v[82:83], v[150:151], v[2:3]
	v_and_b32_e32 v201, 0xffff0000, v202
	v_lshlrev_b32_e32 v202, 16, v203
	v_pk_fma_f32 v[156:157], v[124:125], v[158:159], v[156:157]
	v_pk_fma_f32 v[2:3], v[84:85], v[152:153], v[2:3]
	v_and_b32_e32 v203, 0xffff0000, v203
	v_pk_fma_f32 v[156:157], v[126:127], v[164:165], v[156:157]
	v_pk_fma_f32 v[2:3], v[86:87], v[4:5], v[2:3]
	v_pk_fma_f32 v[156:157], v[120:121], v[148:149], v[156:157]
	v_pk_fma_f32 v[2:3], v[88:89], v[6:7], v[2:3]
	v_pk_fma_f32 v[156:157], v[80:81], v[150:151], v[156:157]
	v_pk_fma_f32 v[2:3], v[90:91], v[8:9], v[2:3]
	v_pk_fma_f32 v[156:157], v[82:83], v[152:153], v[156:157]
	v_pk_fma_f32 v[2:3], v[92:93], v[154:155], v[2:3]
	v_pk_fma_f32 v[156:157], v[84:85], v[4:5], v[156:157]
	v_pk_fma_f32 v[2:3], v[94:95], v[160:161], v[2:3]
	v_pk_fma_f32 v[156:157], v[86:87], v[6:7], v[156:157]
	v_pk_fma_f32 v[2:3], v[96:97], v[162:163], v[2:3]
	v_pk_fma_f32 v[156:157], v[88:89], v[8:9], v[156:157]
	v_pk_fma_f32 v[2:3], v[98:99], v[166:167], v[2:3]
	v_pk_fma_f32 v[156:157], v[90:91], v[154:155], v[156:157]
	v_pk_fma_f32 v[2:3], v[100:101], v[168:169], v[2:3]
	v_pk_fma_f32 v[156:157], v[92:93], v[160:161], v[156:157]
	v_pk_fma_f32 v[2:3], v[102:103], v[170:171], v[2:3]
	v_pk_fma_f32 v[156:157], v[94:95], v[162:163], v[156:157]
	v_pk_fma_f32 v[2:3], v[104:105], v[172:173], v[2:3]
	v_pk_fma_f32 v[156:157], v[96:97], v[166:167], v[156:157]
	v_pk_fma_f32 v[2:3], v[106:107], v[174:175], v[2:3]
	v_pk_fma_f32 v[156:157], v[98:99], v[168:169], v[156:157]
	v_pk_fma_f32 v[2:3], v[108:109], v[176:177], v[2:3]
	v_pk_fma_f32 v[156:157], v[100:101], v[170:171], v[156:157]
	v_pk_fma_f32 v[2:3], v[110:111], v[178:179], v[2:3]
	v_pk_fma_f32 v[156:157], v[102:103], v[172:173], v[156:157]
	v_pk_fma_f32 v[2:3], v[112:113], v[180:181], v[2:3]
	v_pk_fma_f32 v[156:157], v[104:105], v[174:175], v[156:157]
; DI void conv_item(const Params& p, char* lds, int t0, int tid) {
;     ...
; #pragma unroll
;     for (int i = 0; i < 8; ++i) {
;       float a = bias.x, b = bias.y;
; #pragma unroll
;       for (int j = 0; j < 31; ++j) { a += wa[j] * za[i + j]; b += wb[j] * zb[i + j]; }
;       ya[i] = a; yb[i] = b;
;     }
; #pragma unroll
;     for (int i = 0; i < 8; ++i) {
;       float s1 = wave_sum(ya[i] + yb[i]);
;       float s2 = wave_sum(ya[i] * ya[i] + yb[i] * yb[i]);
;       if (lane == 0) { red[(w * 8 + i) * 2] = s1; red[(w * 8 + i) * 2 + 1] = s2; }
;     }
	v_pk_fma_f32 v[2:3], v[114:115], v[182:183], v[2:3]
	v_pk_fma_f32 v[156:157], v[106:107], v[176:177], v[156:157]
	v_pk_fma_f32 v[2:3], v[116:117], v[184:185], v[2:3]
	v_pk_fma_f32 v[156:157], v[108:109], v[178:179], v[156:157]
	v_pk_fma_f32 v[2:3], v[118:119], v[186:187], v[2:3]
	v_pk_fma_f32 v[156:157], v[110:111], v[180:181], v[156:157]
	v_pk_fma_f32 v[2:3], v[130:131], v[188:189], v[2:3]
	v_pk_fma_f32 v[156:157], v[112:113], v[182:183], v[156:157]
	v_pk_fma_f32 v[2:3], v[132:133], v[190:191], v[2:3]
	v_pk_fma_f32 v[156:157], v[114:115], v[184:185], v[156:157]
	v_pk_fma_f32 v[2:3], v[134:135], v[192:193], v[2:3]
	v_pk_fma_f32 v[156:157], v[116:117], v[186:187], v[156:157]
	v_pk_fma_f32 v[2:3], v[136:137], v[194:195], v[2:3]
	v_pk_fma_f32 v[156:157], v[118:119], v[188:189], v[156:157]
	v_pk_fma_f32 v[2:3], v[138:139], v[196:197], v[2:3]
	v_pk_fma_f32 v[156:157], v[130:131], v[190:191], v[156:157]
	v_pk_fma_f32 v[2:3], v[140:141], v[198:199], v[2:3]
	v_pk_fma_f32 v[156:157], v[132:133], v[192:193], v[156:157]
	v_pk_fma_f32 v[2:3], v[142:143], v[200:201], v[2:3]
	v_pk_fma_f32 v[156:157], v[134:135], v[194:195], v[156:157]
	s_nop 0
	v_pk_fma_f32 v[156:157], v[136:137], v[196:197], v[156:157]
	s_nop 0
	v_pk_fma_f32 v[156:157], v[138:139], v[198:199], v[156:157]
	s_nop 0
	v_pk_fma_f32 v[156:157], v[140:141], v[200:201], v[156:157]
	s_nop 0
	v_pk_fma_f32 v[156:157], v[142:143], v[202:203], v[156:157]
	s_nop 0
	v_pk_mul_f32 v[244:245], v[2:3], v[2:3]
	v_add_f32_e32 v240, v2, v3
	v_add_f32_e32 v241, v244, v245
	ds_bpermute_b32 v242, v222, v240
	ds_bpermute_b32 v243, v222, v241
	s_waitcnt lgkmcnt(0)
	v_pk_add_f32 v[240:241], v[240:241], v[242:243]
	ds_bpermute_b32 v242, v223, v240
	ds_bpermute_b32 v243, v223, v241
	s_waitcnt lgkmcnt(0)
	v_pk_add_f32 v[240:241], v[240:241], v[242:243]
	ds_bpermute_b32 v242, v224, v240
	ds_bpermute_b32 v243, v224, v241
	s_waitcnt lgkmcnt(0)
	v_pk_add_f32 v[240:241], v[240:241], v[242:243]
	ds_bpermute_b32 v242, v225, v240
	ds_bpermute_b32 v243, v225, v241
	s_waitcnt lgkmcnt(0)
	v_pk_add_f32 v[240:241], v[240:241], v[242:243]
	ds_bpermute_b32 v242, v226, v240
	ds_bpermute_b32 v243, v226, v241
	s_waitcnt lgkmcnt(0)
	v_pk_add_f32 v[240:241], v[240:241], v[242:243]
	ds_bpermute_b32 v242, v227, v240
	ds_bpermute_b32 v243, v227, v241
	s_waitcnt lgkmcnt(0)
	v_pk_add_f32 v[240:241], v[240:241], v[242:243]
	s_and_saveexec_b64 s[6:7], s[4:5]
	ds_write_b64 v228, v[240:241] offset:63488
	s_or_b64 exec, exec, s[6:7]
	v_pk_mul_f32 v[244:245], v[156:157], v[156:157]
	v_add_f32_e32 v240, v156, v157
	v_add_f32_e32 v241, v244, v245
	ds_bpermute_b32 v242, v222, v240
	ds_bpermute_b32 v243, v222, v241
	s_waitcnt lgkmcnt(0)
	v_pk_add_f32 v[240:241], v[240:241], v[242:243]
	ds_bpermute_b32 v242, v223, v240
	ds_bpermute_b32 v243, v223, v241
	s_waitcnt lgkmcnt(0)
	v_pk_add_f32 v[240:241], v[240:241], v[242:243]
	ds_bpermute_b32 v242, v224, v240
	ds_bpermute_b32 v243, v224, v241
	s_waitcnt lgkmcnt(0)
	v_pk_add_f32 v[240:241], v[240:241], v[242:243]
	ds_bpermute_b32 v242, v225, v240
	ds_bpermute_b32 v243, v225, v241
	s_waitcnt lgkmcnt(0)
	v_pk_add_f32 v[240:241], v[240:241], v[242:243]
	ds_bpermute_b32 v242, v226, v240
	ds_bpermute_b32 v243, v226, v241
	s_waitcnt lgkmcnt(0)
	v_pk_add_f32 v[240:241], v[240:241], v[242:243]
	ds_bpermute_b32 v242, v227, v240
	ds_bpermute_b32 v243, v227, v241
	s_waitcnt lgkmcnt(0)
	v_pk_add_f32 v[240:241], v[240:241], v[242:243]
	s_and_saveexec_b64 s[6:7], s[4:5]
	ds_write_b64 v228, v[240:241] offset:63496
	s_or_b64 exec, exec, s[6:7]
	v_pk_fma_f32 v[158:159], v[122:123], v[158:159], v[128:129]
	v_lshlrev_b32_e32 v206, 16, v208
	v_pk_fma_f32 v[158:159], v[124:125], v[164:165], v[158:159]
	v_pk_fma_f32 v[164:165], v[122:123], v[164:165], v[128:129]
	v_and_b32_e32 v207, 0xffff0000, v208
	v_pk_fma_f32 v[158:159], v[126:127], v[148:149], v[158:159]
	v_lshlrev_b32_e32 v208, 16, v209
	v_pk_fma_f32 v[164:165], v[124:125], v[148:149], v[164:165]
	v_pk_fma_f32 v[158:159], v[120:121], v[150:151], v[158:159]
	v_and_b32_e32 v209, 0xffff0000, v209
	v_pk_fma_f32 v[164:165], v[126:127], v[150:151], v[164:165]
	v_pk_fma_f32 v[158:159], v[80:81], v[152:153], v[158:159]
	v_pk_fma_f32 v[164:165], v[120:121], v[152:153], v[164:165]
	v_pk_fma_f32 v[158:159], v[82:83], v[4:5], v[158:159]
	v_pk_fma_f32 v[164:165], v[80:81], v[4:5], v[164:165]
	v_pk_fma_f32 v[158:159], v[84:85], v[6:7], v[158:159]
	v_pk_fma_f32 v[164:165], v[82:83], v[6:7], v[164:165]
	v_pk_fma_f32 v[158:159], v[86:87], v[8:9], v[158:159]
	v_pk_fma_f32 v[164:165], v[84:85], v[8:9], v[164:165]
	v_pk_fma_f32 v[158:159], v[88:89], v[154:155], v[158:159]
	v_pk_fma_f32 v[164:165], v[86:87], v[154:155], v[164:165]
	v_pk_fma_f32 v[158:159], v[90:91], v[160:161], v[158:159]
	v_pk_fma_f32 v[164:165], v[88:89], v[160:161], v[164:165]
	v_pk_fma_f32 v[158:159], v[92:93], v[162:163], v[158:159]
	v_pk_fma_f32 v[164:165], v[90:91], v[162:163], v[164:165]
	v_pk_fma_f32 v[158:159], v[94:95], v[166:167], v[158:159]
	v_pk_fma_f32 v[164:165], v[92:93], v[166:167], v[164:165]
	v_pk_fma_f32 v[158:159], v[96:97], v[168:169], v[158:159]
	v_pk_fma_f32 v[164:165], v[94:95], v[168:169], v[164:165]
	v_pk_fma_f32 v[158:159], v[98:99], v[170:171], v[158:159]
	v_pk_fma_f32 v[164:165], v[96:97], v[170:171], v[164:165]
	v_pk_fma_f32 v[158:159], v[100:101], v[172:173], v[158:159]
	v_pk_fma_f32 v[164:165], v[98:99], v[172:173], v[164:165]
	v_pk_fma_f32 v[158:159], v[102:103], v[174:175], v[158:159]
	v_pk_fma_f32 v[164:165], v[100:101], v[174:175], v[164:165]
	v_pk_fma_f32 v[158:159], v[104:105], v[176:177], v[158:159]
	v_pk_fma_f32 v[164:165], v[102:103], v[176:177], v[164:165]
; DI void conv_item(const Params& p, char* lds, int t0, int tid) {
;     ...
; #pragma unroll
;     for (int i = 0; i < 8; ++i) {
;       float a = bias.x, b = bias.y;
; #pragma unroll
;       for (int j = 0; j < 31; ++j) { a += wa[j] * za[i + j]; b += wb[j] * zb[i + j]; }
;       ya[i] = a; yb[i] = b;
;     }
; #pragma unroll
;     for (int i = 0; i < 8; ++i) {
;       float s1 = wave_sum(ya[i] + yb[i]);
;       float s2 = wave_sum(ya[i] * ya[i] + yb[i] * yb[i]);
;       if (lane == 0) { red[(w * 8 + i) * 2] = s1; red[(w * 8 + i) * 2 + 1] = s2; }
;     }
	v_pk_fma_f32 v[158:159], v[106:107], v[178:179], v[158:159]
	v_pk_fma_f32 v[164:165], v[104:105], v[178:179], v[164:165]
	v_pk_fma_f32 v[158:159], v[108:109], v[180:181], v[158:159]
	v_pk_fma_f32 v[164:165], v[106:107], v[180:181], v[164:165]
	v_pk_fma_f32 v[158:159], v[110:111], v[182:183], v[158:159]
	v_pk_fma_f32 v[164:165], v[108:109], v[182:183], v[164:165]
	v_pk_fma_f32 v[158:159], v[112:113], v[184:185], v[158:159]
	v_pk_fma_f32 v[164:165], v[110:111], v[184:185], v[164:165]
	v_pk_fma_f32 v[158:159], v[114:115], v[186:187], v[158:159]
	v_pk_fma_f32 v[164:165], v[112:113], v[186:187], v[164:165]
	v_pk_fma_f32 v[158:159], v[116:117], v[188:189], v[158:159]
	v_pk_fma_f32 v[164:165], v[114:115], v[188:189], v[164:165]
	v_pk_fma_f32 v[158:159], v[118:119], v[190:191], v[158:159]
	v_pk_fma_f32 v[164:165], v[116:117], v[190:191], v[164:165]
	v_pk_fma_f32 v[158:159], v[130:131], v[192:193], v[158:159]
	v_pk_fma_f32 v[164:165], v[118:119], v[192:193], v[164:165]
	v_pk_fma_f32 v[158:159], v[132:133], v[194:195], v[158:159]
	v_pk_fma_f32 v[164:165], v[130:131], v[194:195], v[164:165]
	v_pk_fma_f32 v[158:159], v[134:135], v[196:197], v[158:159]
	v_pk_fma_f32 v[164:165], v[132:133], v[196:197], v[164:165]
	v_pk_fma_f32 v[158:159], v[136:137], v[198:199], v[158:159]
	v_pk_fma_f32 v[164:165], v[134:135], v[198:199], v[164:165]
	v_pk_fma_f32 v[158:159], v[138:139], v[200:201], v[158:159]
	v_pk_fma_f32 v[164:165], v[136:137], v[200:201], v[164:165]
	v_pk_fma_f32 v[158:159], v[140:141], v[202:203], v[158:159]
	v_pk_fma_f32 v[164:165], v[138:139], v[202:203], v[164:165]
	v_pk_fma_f32 v[158:159], v[142:143], v[206:207], v[158:159]
	v_pk_fma_f32 v[164:165], v[140:141], v[206:207], v[164:165]
	s_nop 0
	v_pk_fma_f32 v[164:165], v[142:143], v[208:209], v[164:165]
	s_nop 0
	v_pk_mul_f32 v[244:245], v[158:159], v[158:159]
	v_add_f32_e32 v240, v158, v159
	v_add_f32_e32 v241, v244, v245
	ds_bpermute_b32 v242, v222, v240
	ds_bpermute_b32 v243, v222, v241
	s_waitcnt lgkmcnt(0)
	v_pk_add_f32 v[240:241], v[240:241], v[242:243]
	ds_bpermute_b32 v242, v223, v240
	ds_bpermute_b32 v243, v223, v241
	s_waitcnt lgkmcnt(0)
	v_pk_add_f32 v[240:241], v[240:241], v[242:243]
	ds_bpermute_b32 v242, v224, v240
	ds_bpermute_b32 v243, v224, v241
	s_waitcnt lgkmcnt(0)
	v_pk_add_f32 v[240:241], v[240:241], v[242:243]
	ds_bpermute_b32 v242, v225, v240
	ds_bpermute_b32 v243, v225, v241
	s_waitcnt lgkmcnt(0)
	v_pk_add_f32 v[240:241], v[240:241], v[242:243]
	ds_bpermute_b32 v242, v226, v240
	ds_bpermute_b32 v243, v226, v241
	s_waitcnt lgkmcnt(0)
	v_pk_add_f32 v[240:241], v[240:241], v[242:243]
	ds_bpermute_b32 v242, v227, v240
	ds_bpermute_b32 v243, v227, v241
	s_waitcnt lgkmcnt(0)
	v_pk_add_f32 v[240:241], v[240:241], v[242:243]
	s_and_saveexec_b64 s[6:7], s[4:5]
	ds_write_b64 v228, v[240:241] offset:63504
	s_or_b64 exec, exec, s[6:7]
	v_pk_mul_f32 v[244:245], v[164:165], v[164:165]
	v_add_f32_e32 v240, v164, v165
	v_add_f32_e32 v241, v244, v245
	ds_bpermute_b32 v242, v222, v240
	ds_bpermute_b32 v243, v222, v241
	s_waitcnt lgkmcnt(0)
	v_pk_add_f32 v[240:241], v[240:241], v[242:243]
	ds_bpermute_b32 v242, v223, v240
	ds_bpermute_b32 v243, v223, v241
	s_waitcnt lgkmcnt(0)
	v_pk_add_f32 v[240:241], v[240:241], v[242:243]
	ds_bpermute_b32 v242, v224, v240
	ds_bpermute_b32 v243, v224, v241
	s_waitcnt lgkmcnt(0)
	v_pk_add_f32 v[240:241], v[240:241], v[242:243]
	ds_bpermute_b32 v242, v225, v240
	ds_bpermute_b32 v243, v225, v241
	s_waitcnt lgkmcnt(0)
	v_pk_add_f32 v[240:241], v[240:241], v[242:243]
	ds_bpermute_b32 v242, v226, v240
	ds_bpermute_b32 v243, v226, v241
	s_waitcnt lgkmcnt(0)
	v_pk_add_f32 v[240:241], v[240:241], v[242:243]
	ds_bpermute_b32 v242, v227, v240
	ds_bpermute_b32 v243, v227, v241
	s_waitcnt lgkmcnt(0)
	v_pk_add_f32 v[240:241], v[240:241], v[242:243]
	s_and_saveexec_b64 s[6:7], s[4:5]
	ds_write_b64 v228, v[240:241] offset:63512
	s_or_b64 exec, exec, s[6:7]
	v_pk_fma_f32 v[148:149], v[122:123], v[148:149], v[128:129]
	v_lshlrev_b32_e32 v212, 16, v210
	v_pk_fma_f32 v[148:149], v[124:125], v[150:151], v[148:149]
	v_pk_fma_f32 v[150:151], v[122:123], v[150:151], v[128:129]
	v_and_b32_e32 v213, 0xffff0000, v210
	v_pk_fma_f32 v[148:149], v[126:127], v[152:153], v[148:149]
	v_lshlrev_b32_e32 v210, 16, v211
	v_pk_fma_f32 v[150:151], v[124:125], v[152:153], v[150:151]
	v_pk_fma_f32 v[148:149], v[120:121], v[4:5], v[148:149]
	v_and_b32_e32 v211, 0xffff0000, v211
	v_pk_fma_f32 v[150:151], v[126:127], v[4:5], v[150:151]
	v_pk_fma_f32 v[148:149], v[80:81], v[6:7], v[148:149]
	v_pk_fma_f32 v[150:151], v[120:121], v[6:7], v[150:151]
	v_pk_fma_f32 v[148:149], v[82:83], v[8:9], v[148:149]
	v_pk_fma_f32 v[150:151], v[80:81], v[8:9], v[150:151]
	v_pk_fma_f32 v[148:149], v[84:85], v[154:155], v[148:149]
	v_pk_fma_f32 v[150:151], v[82:83], v[154:155], v[150:151]
	v_pk_fma_f32 v[148:149], v[86:87], v[160:161], v[148:149]
	v_pk_fma_f32 v[150:151], v[84:85], v[160:161], v[150:151]
	v_pk_fma_f32 v[148:149], v[88:89], v[162:163], v[148:149]
	v_pk_fma_f32 v[150:151], v[86:87], v[162:163], v[150:151]
	v_pk_fma_f32 v[148:149], v[90:91], v[166:167], v[148:149]
	v_pk_fma_f32 v[150:151], v[88:89], v[166:167], v[150:151]
	v_pk_fma_f32 v[148:149], v[92:93], v[168:169], v[148:149]
	v_pk_fma_f32 v[150:151], v[90:91], v[168:169], v[150:151]
	v_pk_fma_f32 v[148:149], v[94:95], v[170:171], v[148:149]
	v_pk_fma_f32 v[150:151], v[92:93], v[170:171], v[150:151]
	v_pk_fma_f32 v[148:149], v[96:97], v[172:173], v[148:149]
	v_pk_fma_f32 v[150:151], v[94:95], v[172:173], v[150:151]
	v_pk_fma_f32 v[148:149], v[98:99], v[174:175], v[148:149]
	v_pk_fma_f32 v[150:151], v[96:97], v[174:175], v[150:151]
; DI void conv_item(const Params& p, char* lds, int t0, int tid) {
;     ...
;     for (int i = 0; i < 8; ++i) {
;       float a = bias.x, b = bias.y;
; #pragma unroll
;       for (int j = 0; j < 31; ++j) { a += wa[j] * za[i + j]; b += wb[j] * zb[i + j]; }
;       ya[i] = a; yb[i] = b;
;     }
; #pragma unroll
;     for (int i = 0; i < 8; ++i) {
;       float s1 = wave_sum(ya[i] + yb[i]);
;       float s2 = wave_sum(ya[i] * ya[i] + yb[i] * yb[i]);
;       if (lane == 0) { red[(w * 8 + i) * 2] = s1; red[(w * 8 + i) * 2 + 1] = s2; }
;     }
	v_pk_fma_f32 v[148:149], v[100:101], v[176:177], v[148:149]
	v_pk_fma_f32 v[150:151], v[98:99], v[176:177], v[150:151]
	v_pk_fma_f32 v[148:149], v[102:103], v[178:179], v[148:149]
	v_pk_fma_f32 v[150:151], v[100:101], v[178:179], v[150:151]
	v_pk_fma_f32 v[148:149], v[104:105], v[180:181], v[148:149]
	v_pk_fma_f32 v[150:151], v[102:103], v[180:181], v[150:151]
	v_pk_fma_f32 v[148:149], v[106:107], v[182:183], v[148:149]
	v_pk_fma_f32 v[150:151], v[104:105], v[182:183], v[150:151]
	v_pk_fma_f32 v[148:149], v[108:109], v[184:185], v[148:149]
	v_pk_fma_f32 v[150:151], v[106:107], v[184:185], v[150:151]
	v_pk_fma_f32 v[148:149], v[110:111], v[186:187], v[148:149]
	v_pk_fma_f32 v[150:151], v[108:109], v[186:187], v[150:151]
	v_pk_fma_f32 v[148:149], v[112:113], v[188:189], v[148:149]
	v_pk_fma_f32 v[150:151], v[110:111], v[188:189], v[150:151]
	v_pk_fma_f32 v[148:149], v[114:115], v[190:191], v[148:149]
	v_pk_fma_f32 v[150:151], v[112:113], v[190:191], v[150:151]
	v_pk_fma_f32 v[148:149], v[116:117], v[192:193], v[148:149]
	v_pk_fma_f32 v[150:151], v[114:115], v[192:193], v[150:151]
	v_pk_fma_f32 v[148:149], v[118:119], v[194:195], v[148:149]
	v_pk_fma_f32 v[150:151], v[116:117], v[194:195], v[150:151]
	v_pk_fma_f32 v[148:149], v[130:131], v[196:197], v[148:149]
	v_pk_fma_f32 v[150:151], v[118:119], v[196:197], v[150:151]
	v_pk_fma_f32 v[148:149], v[132:133], v[198:199], v[148:149]
	v_pk_fma_f32 v[150:151], v[130:131], v[198:199], v[150:151]
	v_pk_fma_f32 v[148:149], v[134:135], v[200:201], v[148:149]
	v_pk_fma_f32 v[150:151], v[132:133], v[200:201], v[150:151]
	v_pk_fma_f32 v[148:149], v[136:137], v[202:203], v[148:149]
	v_pk_fma_f32 v[150:151], v[134:135], v[202:203], v[150:151]
	v_pk_fma_f32 v[148:149], v[138:139], v[206:207], v[148:149]
	v_pk_fma_f32 v[150:151], v[136:137], v[206:207], v[150:151]
	v_pk_fma_f32 v[148:149], v[140:141], v[208:209], v[148:149]
	v_pk_fma_f32 v[150:151], v[138:139], v[208:209], v[150:151]
	v_pk_fma_f32 v[148:149], v[142:143], v[212:213], v[148:149]
	v_pk_fma_f32 v[150:151], v[140:141], v[212:213], v[150:151]
	s_nop 0
	v_pk_fma_f32 v[150:151], v[142:143], v[210:211], v[150:151]
	s_nop 0
	v_pk_mul_f32 v[244:245], v[148:149], v[148:149]
	v_add_f32_e32 v240, v148, v149
	v_add_f32_e32 v241, v244, v245
	ds_bpermute_b32 v242, v222, v240
	ds_bpermute_b32 v243, v222, v241
	s_waitcnt lgkmcnt(0)
	v_pk_add_f32 v[240:241], v[240:241], v[242:243]
	ds_bpermute_b32 v242, v223, v240
	ds_bpermute_b32 v243, v223, v241
	s_waitcnt lgkmcnt(0)
	v_pk_add_f32 v[240:241], v[240:241], v[242:243]
	ds_bpermute_b32 v242, v224, v240
	ds_bpermute_b32 v243, v224, v241
	s_waitcnt lgkmcnt(0)
	v_pk_add_f32 v[240:241], v[240:241], v[242:243]
	ds_bpermute_b32 v242, v225, v240
	ds_bpermute_b32 v243, v225, v241
	s_waitcnt lgkmcnt(0)
	v_pk_add_f32 v[240:241], v[240:241], v[242:243]
	ds_bpermute_b32 v242, v226, v240
	ds_bpermute_b32 v243, v226, v241
	s_waitcnt lgkmcnt(0)
	v_pk_add_f32 v[240:241], v[240:241], v[242:243]
	ds_bpermute_b32 v242, v227, v240
	ds_bpermute_b32 v243, v227, v241
	s_waitcnt lgkmcnt(0)
	v_pk_add_f32 v[240:241], v[240:241], v[242:243]
	s_and_saveexec_b64 s[6:7], s[4:5]
	ds_write_b64 v228, v[240:241] offset:63520
	s_or_b64 exec, exec, s[6:7]
	v_pk_mul_f32 v[244:245], v[150:151], v[150:151]
	v_add_f32_e32 v240, v150, v151
	v_add_f32_e32 v241, v244, v245
	ds_bpermute_b32 v242, v222, v240
	ds_bpermute_b32 v243, v222, v241
	s_waitcnt lgkmcnt(0)
	v_pk_add_f32 v[240:241], v[240:241], v[242:243]
	ds_bpermute_b32 v242, v223, v240
	ds_bpermute_b32 v243, v223, v241
	s_waitcnt lgkmcnt(0)
	v_pk_add_f32 v[240:241], v[240:241], v[242:243]
	ds_bpermute_b32 v242, v224, v240
	ds_bpermute_b32 v243, v224, v241
	s_waitcnt lgkmcnt(0)
	v_pk_add_f32 v[240:241], v[240:241], v[242:243]
	ds_bpermute_b32 v242, v225, v240
	ds_bpermute_b32 v243, v225, v241
	s_waitcnt lgkmcnt(0)
	v_pk_add_f32 v[240:241], v[240:241], v[242:243]
	ds_bpermute_b32 v242, v226, v240
	ds_bpermute_b32 v243, v226, v241
	s_waitcnt lgkmcnt(0)
	v_pk_add_f32 v[240:241], v[240:241], v[242:243]
	ds_bpermute_b32 v242, v227, v240
	ds_bpermute_b32 v243, v227, v241
	s_waitcnt lgkmcnt(0)
; DI void conv_item(const Params& p, char* lds, int t0, int tid) {
;     ...
;     for (int i = 0; i < 8; ++i) {
;       float a = bias.x, b = bias.y;
; #pragma unroll
;       for (int j = 0; j < 31; ++j) { a += wa[j] * za[i + j]; b += wb[j] * zb[i + j]; }
;       ya[i] = a; yb[i] = b;
;     }
; #pragma unroll
;     for (int i = 0; i < 8; ++i) {
;       float s1 = wave_sum(ya[i] + yb[i]);
;       float s2 = wave_sum(ya[i] * ya[i] + yb[i] * yb[i]);
;       if (lane == 0) { red[(w * 8 + i) * 2] = s1; red[(w * 8 + i) * 2 + 1] = s2; }
;     }
	v_pk_add_f32 v[240:241], v[240:241], v[242:243]
	s_and_saveexec_b64 s[6:7], s[4:5]
	ds_write_b64 v228, v[240:241] offset:63528
	s_or_b64 exec, exec, s[6:7]
	v_pk_fma_f32 v[152:153], v[122:123], v[152:153], v[128:129]
	v_lshlrev_b32_e32 v214, 16, v204
	v_pk_fma_f32 v[152:153], v[124:125], v[4:5], v[152:153]
	v_pk_fma_f32 v[4:5], v[122:123], v[4:5], v[128:129]
	v_and_b32_e32 v215, 0xffff0000, v204
	v_pk_fma_f32 v[152:153], v[126:127], v[6:7], v[152:153]
	v_lshlrev_b32_e32 v204, 16, v205
	v_pk_fma_f32 v[4:5], v[124:125], v[6:7], v[4:5]
	v_pk_fma_f32 v[152:153], v[120:121], v[8:9], v[152:153]
	v_and_b32_e32 v205, 0xffff0000, v205
	v_pk_fma_f32 v[4:5], v[126:127], v[8:9], v[4:5]
	v_pk_fma_f32 v[152:153], v[80:81], v[154:155], v[152:153]
	v_pk_fma_f32 v[4:5], v[120:121], v[154:155], v[4:5]
	v_pk_fma_f32 v[152:153], v[82:83], v[160:161], v[152:153]
	v_pk_fma_f32 v[4:5], v[80:81], v[160:161], v[4:5]
	v_pk_fma_f32 v[152:153], v[84:85], v[162:163], v[152:153]
	v_pk_fma_f32 v[4:5], v[82:83], v[162:163], v[4:5]
	v_pk_fma_f32 v[152:153], v[86:87], v[166:167], v[152:153]
	v_pk_fma_f32 v[4:5], v[84:85], v[166:167], v[4:5]
	v_pk_fma_f32 v[152:153], v[88:89], v[168:169], v[152:153]
	v_pk_fma_f32 v[4:5], v[86:87], v[168:169], v[4:5]
	v_pk_fma_f32 v[152:153], v[90:91], v[170:171], v[152:153]
	v_pk_fma_f32 v[4:5], v[88:89], v[170:171], v[4:5]
	v_pk_fma_f32 v[152:153], v[92:93], v[172:173], v[152:153]
	v_pk_fma_f32 v[4:5], v[90:91], v[172:173], v[4:5]
	v_pk_fma_f32 v[152:153], v[94:95], v[174:175], v[152:153]
	v_pk_fma_f32 v[4:5], v[92:93], v[174:175], v[4:5]
	v_pk_fma_f32 v[152:153], v[96:97], v[176:177], v[152:153]
	v_pk_fma_f32 v[4:5], v[94:95], v[176:177], v[4:5]
	v_pk_fma_f32 v[152:153], v[98:99], v[178:179], v[152:153]
	v_pk_fma_f32 v[4:5], v[96:97], v[178:179], v[4:5]
	v_pk_fma_f32 v[152:153], v[100:101], v[180:181], v[152:153]
	v_pk_fma_f32 v[4:5], v[98:99], v[180:181], v[4:5]
	v_pk_fma_f32 v[152:153], v[102:103], v[182:183], v[152:153]
	v_pk_fma_f32 v[4:5], v[100:101], v[182:183], v[4:5]
	v_pk_fma_f32 v[152:153], v[104:105], v[184:185], v[152:153]
	v_pk_fma_f32 v[4:5], v[102:103], v[184:185], v[4:5]
	v_pk_fma_f32 v[152:153], v[106:107], v[186:187], v[152:153]
	v_pk_fma_f32 v[4:5], v[104:105], v[186:187], v[4:5]
	v_pk_fma_f32 v[152:153], v[108:109], v[188:189], v[152:153]
	v_pk_fma_f32 v[4:5], v[106:107], v[188:189], v[4:5]
	v_pk_fma_f32 v[152:153], v[110:111], v[190:191], v[152:153]
	v_pk_fma_f32 v[4:5], v[108:109], v[190:191], v[4:5]
	v_pk_fma_f32 v[152:153], v[112:113], v[192:193], v[152:153]
	v_pk_fma_f32 v[4:5], v[110:111], v[192:193], v[4:5]
	v_pk_fma_f32 v[152:153], v[114:115], v[194:195], v[152:153]
	v_pk_fma_f32 v[4:5], v[112:113], v[194:195], v[4:5]
	v_pk_fma_f32 v[152:153], v[116:117], v[196:197], v[152:153]
	v_pk_fma_f32 v[4:5], v[114:115], v[196:197], v[4:5]
	v_pk_fma_f32 v[152:153], v[118:119], v[198:199], v[152:153]
	v_pk_fma_f32 v[4:5], v[116:117], v[198:199], v[4:5]
	v_pk_fma_f32 v[152:153], v[130:131], v[200:201], v[152:153]
	v_pk_fma_f32 v[4:5], v[118:119], v[200:201], v[4:5]
	v_pk_fma_f32 v[152:153], v[132:133], v[202:203], v[152:153]
	v_pk_fma_f32 v[4:5], v[130:131], v[202:203], v[4:5]
	v_pk_fma_f32 v[152:153], v[134:135], v[206:207], v[152:153]
	v_pk_fma_f32 v[4:5], v[132:133], v[206:207], v[4:5]
	v_pk_fma_f32 v[152:153], v[136:137], v[208:209], v[152:153]
	v_pk_fma_f32 v[4:5], v[134:135], v[208:209], v[4:5]
	v_pk_fma_f32 v[152:153], v[138:139], v[212:213], v[152:153]
	v_pk_fma_f32 v[4:5], v[136:137], v[212:213], v[4:5]
	v_pk_fma_f32 v[152:153], v[140:141], v[210:211], v[152:153]
	v_pk_fma_f32 v[4:5], v[138:139], v[210:211], v[4:5]
	v_pk_fma_f32 v[152:153], v[142:143], v[214:215], v[152:153]
	v_pk_fma_f32 v[4:5], v[140:141], v[214:215], v[4:5]
	s_nop 0
	v_pk_fma_f32 v[154:155], v[142:143], v[204:205], v[4:5]
	s_nop 0
	v_pk_mul_f32 v[244:245], v[152:153], v[152:153]
	v_add_f32_e32 v240, v152, v153
	v_add_f32_e32 v241, v244, v245
	ds_bpermute_b32 v242, v222, v240
	ds_bpermute_b32 v243, v222, v241
	s_waitcnt lgkmcnt(0)
	v_pk_add_f32 v[240:241], v[240:241], v[242:243]
	ds_bpermute_b32 v242, v223, v240
	ds_bpermute_b32 v243, v223, v241
	s_waitcnt lgkmcnt(0)
	v_pk_add_f32 v[240:241], v[240:241], v[242:243]
	ds_bpermute_b32 v242, v224, v240
	ds_bpermute_b32 v243, v224, v241
	s_waitcnt lgkmcnt(0)
	v_pk_add_f32 v[240:241], v[240:241], v[242:243]
	ds_bpermute_b32 v242, v225, v240
	ds_bpermute_b32 v243, v225, v241
	s_waitcnt lgkmcnt(0)
	v_pk_add_f32 v[240:241], v[240:241], v[242:243]
	ds_bpermute_b32 v242, v226, v240
	ds_bpermute_b32 v243, v226, v241
	s_waitcnt lgkmcnt(0)
	v_pk_add_f32 v[240:241], v[240:241], v[242:243]
	ds_bpermute_b32 v242, v227, v240
	ds_bpermute_b32 v243, v227, v241
	s_waitcnt lgkmcnt(0)
	v_pk_add_f32 v[240:241], v[240:241], v[242:243]
	s_and_saveexec_b64 s[6:7], s[4:5]
	ds_write_b64 v228, v[240:241] offset:63536
	s_or_b64 exec, exec, s[6:7]
	v_pk_mul_f32 v[244:245], v[154:155], v[154:155]
	v_add_f32_e32 v240, v154, v155
	v_add_f32_e32 v241, v244, v245
	ds_bpermute_b32 v242, v222, v240
	ds_bpermute_b32 v243, v222, v241
	s_waitcnt lgkmcnt(0)
	v_pk_add_f32 v[240:241], v[240:241], v[242:243]
	ds_bpermute_b32 v242, v223, v240
	ds_bpermute_b32 v243, v223, v241
	s_waitcnt lgkmcnt(0)
	v_pk_add_f32 v[240:241], v[240:241], v[242:243]
	ds_bpermute_b32 v242, v224, v240
	ds_bpermute_b32 v243, v224, v241
	s_waitcnt lgkmcnt(0)
	v_pk_add_f32 v[240:241], v[240:241], v[242:243]
	ds_bpermute_b32 v242, v225, v240
	ds_bpermute_b32 v243, v225, v241
	s_waitcnt lgkmcnt(0)
	v_pk_add_f32 v[240:241], v[240:241], v[242:243]
	ds_bpermute_b32 v242, v226, v240
	ds_bpermute_b32 v243, v226, v241
	s_waitcnt lgkmcnt(0)
	v_pk_add_f32 v[240:241], v[240:241], v[242:243]
	ds_bpermute_b32 v242, v227, v240
	ds_bpermute_b32 v243, v227, v241
	s_waitcnt lgkmcnt(0)
	v_pk_add_f32 v[240:241], v[240:241], v[242:243]
	s_and_saveexec_b64 s[6:7], s[4:5]
	ds_write_b64 v228, v[240:241] offset:63544
	s_branch .LBB0_195
